# v5 (aligned) plus P4 queue-id prefetch: next prompt/GLA unit id fetched by a returning atomic at unit start, collected at unit end
# speedup vs baseline: 1.0004x; 1.0004x over previous
_Z9hymba_fwd4Args:
	s_mov_b32 s98, 0
	s_load_dwordx4 s[36:39], s[0:1], 0xe0
	s_load_dwordx2 s[96:97], s[0:1], 0xf0
	s_load_dword s44, s[0:1], 0xf8
	s_add_u32 s4, s0, 0xf8
	s_addc_u32 s5, s1, 0
	v_lshl_add_u32 v1, v0, 2, 0
	v_writelane_b32 v255, s4, 0
	v_readfirstlane_b32 s95, v0
	v_add_u32_e32 v1, 0x21800, v1
	v_writelane_b32 v255, s5, 1
	s_mov_b32 s4, 0
	s_mov_b32 s5, 1
	s_mov_b64 s[6:7], 0
	v_mov_b32_e32 v2, 0
	s_mov_b32 s8, s4
	s_branch .LBB0_2

.LBB0_185:
	s_ashr_i32 s53, s52, 31
	s_lshl_b64 s[4:5], s[52:53], 19
	s_add_u32 s54, s3, s4
	s_addc_u32 s55, s45, s5
	s_and_b64 s[4:5], s[8:9], exec
	s_cselect_b32 s4, s55, s61
	s_cselect_b32 s5, s54, s60
	s_ashr_i32 s43, s42, 31
	s_lshl_b64 s[46:47], s[42:43], 19
	s_add_u32 s56, s66, s46
	s_addc_u32 s57, s67, s47
	s_and_b64 s[46:47], s[8:9], exec
	s_cselect_b32 s11, s57, s63
	s_cselect_b32 s35, s56, s62
	s_add_u32 s60, s60, 0x40080
	s_addc_u32 s61, s61, 0
	s_add_u32 s43, s62, 0x100
	v_mov_b32_e32 v0, 0
	s_addc_u32 s48, s63, 0
	s_mov_b32 s49, -2
	v_mov_b32_e32 v1, v0
	v_mov_b32_e32 v2, v0
	v_mov_b32_e32 v3, v0
	v_mov_b32_e32 v4, v0
	v_mov_b32_e32 v5, v0
	v_mov_b32_e32 v6, v0
	v_mov_b32_e32 v7, v0
	v_mov_b32_e32 v8, v0
	v_mov_b32_e32 v9, v0
	v_mov_b32_e32 v10, v0
	v_mov_b32_e32 v11, v0
	v_mov_b32_e32 v12, v0
	v_mov_b32_e32 v13, v0
	v_mov_b32_e32 v14, v0
	v_mov_b32_e32 v15, v0
	v_mov_b32_e32 v16, v0
	v_mov_b32_e32 v17, v0
	v_mov_b32_e32 v18, v0
	v_mov_b32_e32 v19, v0
	v_mov_b32_e32 v20, v0
	v_mov_b32_e32 v21, v0
	v_mov_b32_e32 v22, v0
	v_mov_b32_e32 v23, v0
	v_mov_b32_e32 v24, v0
	v_mov_b32_e32 v25, v0
	v_mov_b32_e32 v26, v0
	v_mov_b32_e32 v27, v0
	v_mov_b32_e32 v28, v0
	v_mov_b32_e32 v29, v0
	v_mov_b32_e32 v30, v0
	v_mov_b32_e32 v31, v0
	v_mov_b32_e32 v64, v0
	v_mov_b32_e32 v65, v0
	v_mov_b32_e32 v66, v0
	v_mov_b32_e32 v67, v0
	v_mov_b32_e32 v68, v0
	v_mov_b32_e32 v69, v0
	v_mov_b32_e32 v70, v0
	v_mov_b32_e32 v71, v0
	v_mov_b32_e32 v72, v0
	v_mov_b32_e32 v73, v0
	v_mov_b32_e32 v74, v0
	v_mov_b32_e32 v75, v0
	v_mov_b32_e32 v76, v0
	v_mov_b32_e32 v77, v0
	v_mov_b32_e32 v78, v0
	v_mov_b32_e32 v79, v0
	v_mov_b32_e32 v80, v0
	v_mov_b32_e32 v81, v0
	v_mov_b32_e32 v82, v0
	v_mov_b32_e32 v83, v0
	v_mov_b32_e32 v84, v0
	v_mov_b32_e32 v85, v0
	v_mov_b32_e32 v86, v0
	v_mov_b32_e32 v87, v0
	v_mov_b32_e32 v88, v0
	v_mov_b32_e32 v89, v0
	v_mov_b32_e32 v90, v0
	v_mov_b32_e32 v91, v0
	v_mov_b32_e32 v92, v0
	v_mov_b32_e32 v93, v0
	v_mov_b32_e32 v94, v0
	v_mov_b32_e32 v95, v0
	v_mov_b32_e32 v32, v0
	v_mov_b32_e32 v33, v0
	v_mov_b32_e32 v34, v0
	v_mov_b32_e32 v35, v0
	v_mov_b32_e32 v36, v0
	v_mov_b32_e32 v37, v0
	v_mov_b32_e32 v38, v0
	v_mov_b32_e32 v39, v0
	v_mov_b32_e32 v40, v0
	v_mov_b32_e32 v41, v0
	v_mov_b32_e32 v42, v0
	v_mov_b32_e32 v43, v0
	v_mov_b32_e32 v44, v0
	v_mov_b32_e32 v45, v0
	v_mov_b32_e32 v46, v0
	v_mov_b32_e32 v47, v0
	v_mov_b32_e32 v48, v0
	v_mov_b32_e32 v49, v0
	v_mov_b32_e32 v50, v0
	v_mov_b32_e32 v51, v0
	v_mov_b32_e32 v52, v0
	v_mov_b32_e32 v53, v0
	v_mov_b32_e32 v54, v0
	v_mov_b32_e32 v55, v0
	v_mov_b32_e32 v56, v0
	v_mov_b32_e32 v57, v0
	v_mov_b32_e32 v58, v0
	v_mov_b32_e32 v59, v0
	v_mov_b32_e32 v60, v0
	v_mov_b32_e32 v61, v0
	v_mov_b32_e32 v62, v0
	v_mov_b32_e32 v63, v0
	v_mov_b32_e32 v96, v0
	v_mov_b32_e32 v97, v0
	v_mov_b32_e32 v98, v0
	v_mov_b32_e32 v99, v0
	v_mov_b32_e32 v100, v0
	v_mov_b32_e32 v101, v0
	v_mov_b32_e32 v102, v0
	v_mov_b32_e32 v103, v0
	v_mov_b32_e32 v104, v0
	v_mov_b32_e32 v105, v0
	v_mov_b32_e32 v106, v0
	v_mov_b32_e32 v107, v0
	v_mov_b32_e32 v108, v0
	v_mov_b32_e32 v109, v0
	v_mov_b32_e32 v110, v0
	v_mov_b32_e32 v111, v0
	v_mov_b32_e32 v112, v0
	v_mov_b32_e32 v113, v0
	v_mov_b32_e32 v114, v0
	v_mov_b32_e32 v115, v0
	v_mov_b32_e32 v116, v0
	v_mov_b32_e32 v117, v0
	v_mov_b32_e32 v118, v0
	v_mov_b32_e32 v119, v0
	v_mov_b32_e32 v120, v0
	v_mov_b32_e32 v121, v0
	v_mov_b32_e32 v122, v0
	v_mov_b32_e32 v123, v0
	v_mov_b32_e32 v124, v0
	v_mov_b32_e32 v125, v0
	v_mov_b32_e32 v126, v0
	v_mov_b32_e32 v127, v0
	s_nop 0
	s_nop 0
	s_nop 0
	s_nop 0
	s_nop 0
	s_nop 0
.LBB0_186:
	v_add_u32_e32 v140, s82, v198
	v_add_u32_e32 v160, s83, v198
	ds_read_b128 v[128:131], v140
	ds_read_b128 v[132:135], v140 offset:1024
	ds_read_b128 v[136:139], v140 offset:2048
	ds_read_b128 v[140:143], v140 offset:3072
	ds_read_b128 v[144:147], v160
	ds_read_b128 v[148:151], v160 offset:1024
	ds_read_b128 v[184:187], v160 offset:2048
	ds_read_b128 v[188:191], v160 offset:3072
	s_add_u32 s46, s60, 0xfffc0080
	s_addc_u32 s47, s61, -1
	s_cmp_eq_u32 s49, 12
	s_cselect_b32 s65, s4, s47
	s_cselect_b32 s64, s5, s46
	s_cselect_b32 s63, s11, s48
	s_cselect_b32 s62, s35, s43
	v_lshl_add_u64 v[252:253], s[60:61], 0, v[174:175]
	s_add_i32 m0, s69, 0xc000
	ds_read_b128 v[220:223], v209
	ds_read_b128 v[224:227], v209 offset:1024
	ds_read_b128 v[228:231], v209 offset:2048
	ds_read_b128 v[232:235], v209 offset:3072
	ds_read_b128 v[236:239], v209 offset:4096
	ds_read_b128 v[240:243], v209 offset:5120
	ds_read_b128 v[244:247], v209 offset:6144
	ds_read_b128 v[248:251], v209 offset:7168
	global_load_lds_dwordx4 v[252:253], off
	v_lshl_add_u64 v[252:253], s[60:61], 0, v[176:177]
	s_add_i32 m0, s69, 0xe000
	s_nop 0
	global_load_lds_dwordx4 v[252:253], off
	s_waitcnt vmcnt(8)
	s_waitcnt lgkmcnt(0)
	s_barrier
	s_setprio 1
	s_waitcnt lgkmcnt(0)
	v_mfma_f32_16x16x32_bf16 v[124:127], v[128:131], v[220:223], v[124:127]
	v_mfma_f32_16x16x32_bf16 v[120:123], v[136:139], v[220:223], v[120:123]
	v_mfma_f32_16x16x32_bf16 v[116:119], v[128:131], v[228:231], v[116:119]
	v_mfma_f32_16x16x32_bf16 v[112:115], v[136:139], v[228:231], v[112:115]
	v_mfma_f32_16x16x32_bf16 v[108:111], v[128:131], v[236:239], v[108:111]
	v_mfma_f32_16x16x32_bf16 v[104:107], v[136:139], v[236:239], v[104:107]
	v_mfma_f32_16x16x32_bf16 v[100:103], v[128:131], v[244:247], v[100:103]
	v_mfma_f32_16x16x32_bf16 v[96:99], v[136:139], v[244:247], v[96:99]
	v_mfma_f32_16x16x32_bf16 v[124:127], v[132:135], v[224:227], v[124:127]
	v_mfma_f32_16x16x32_bf16 v[120:123], v[140:143], v[224:227], v[120:123]
	v_mfma_f32_16x16x32_bf16 v[116:119], v[132:135], v[232:235], v[116:119]
	v_mfma_f32_16x16x32_bf16 v[112:115], v[140:143], v[232:235], v[112:115]
	v_mfma_f32_16x16x32_bf16 v[108:111], v[132:135], v[240:243], v[108:111]
	v_mfma_f32_16x16x32_bf16 v[104:107], v[140:143], v[240:243], v[104:107]
	v_mfma_f32_16x16x32_bf16 v[100:103], v[132:135], v[248:251], v[100:103]
	v_mfma_f32_16x16x32_bf16 v[96:99], v[140:143], v[248:251], v[96:99]
	s_setprio 0
	s_setprio 1
	v_mfma_f32_16x16x32_bf16 v[60:63], v[144:147], v[220:223], v[60:63]
	v_mfma_f32_16x16x32_bf16 v[56:59], v[184:187], v[220:223], v[56:59]
	v_mfma_f32_16x16x32_bf16 v[52:55], v[144:147], v[228:231], v[52:55]
	v_mfma_f32_16x16x32_bf16 v[48:51], v[184:187], v[228:231], v[48:51]
	v_mfma_f32_16x16x32_bf16 v[44:47], v[144:147], v[236:239], v[44:47]
	v_mfma_f32_16x16x32_bf16 v[40:43], v[184:187], v[236:239], v[40:43]
	v_mfma_f32_16x16x32_bf16 v[36:39], v[144:147], v[244:247], v[36:39]
	v_mfma_f32_16x16x32_bf16 v[32:35], v[184:187], v[244:247], v[32:35]
	v_mfma_f32_16x16x32_bf16 v[60:63], v[148:151], v[224:227], v[60:63]
	v_mfma_f32_16x16x32_bf16 v[56:59], v[188:191], v[224:227], v[56:59]
	v_mfma_f32_16x16x32_bf16 v[52:55], v[148:151], v[232:235], v[52:55]
	v_mfma_f32_16x16x32_bf16 v[48:51], v[188:191], v[232:235], v[48:51]
	v_mfma_f32_16x16x32_bf16 v[44:47], v[148:151], v[240:243], v[44:47]
	v_mfma_f32_16x16x32_bf16 v[40:43], v[188:191], v[240:243], v[40:43]
	v_mfma_f32_16x16x32_bf16 v[36:39], v[148:151], v[248:251], v[36:39]
	v_mfma_f32_16x16x32_bf16 v[32:35], v[188:191], v[248:251], v[32:35]
	s_setprio 0
	s_barrier
	s_add_i32 s46, s82, s68
	v_lshl_add_u64 v[252:253], s[62:63], 0, v[154:155]
	s_mov_b32 m0, s46
	ds_read_b128 v[220:223], v209 offset:16384
	ds_read_b128 v[224:227], v209 offset:17408
	ds_read_b128 v[228:231], v209 offset:18432
	ds_read_b128 v[232:235], v209 offset:19456
	ds_read_b128 v[236:239], v209 offset:20480
	ds_read_b128 v[240:243], v209 offset:21504
	ds_read_b128 v[244:247], v209 offset:22528
	ds_read_b128 v[248:251], v209 offset:23552
	global_load_lds_dwordx4 v[252:253], off
	s_add_i32 m0, s46, 0x2000
	s_add_u32 s46, s62, 0x40000
	v_lshl_add_u64 v[202:203], s[62:63], 0, v[158:159]
	s_addc_u32 s47, s63, 0
	s_add_i32 s50, s83, s68
	global_load_lds_dwordx4 v[202:203], off
	v_lshl_add_u64 v[204:205], s[46:47], 0, v[154:155]
	s_mov_b32 m0, s50
	v_lshl_add_u64 v[206:207], s[64:65], 0, v[156:157]
	global_load_lds_dwordx4 v[204:205], off
	v_lshl_add_u64 v[204:205], s[46:47], 0, v[158:159]
	s_add_i32 m0, s50, 0x2000
	s_nop 0
	global_load_lds_dwordx4 v[204:205], off
	v_lshl_add_u64 v[204:205], s[64:65], 0, v[152:153]
	s_mov_b32 m0, s69
	s_nop 0
	global_load_lds_dwordx4 v[204:205], off
	s_mov_b32 m0, s70
	s_nop 0
	global_load_lds_dwordx4 v[206:207], off
	s_nop 0
	s_waitcnt vmcnt(8)
	s_waitcnt lgkmcnt(0)
	s_barrier
	s_setprio 1
	s_waitcnt lgkmcnt(0)
	v_mfma_f32_16x16x32_bf16 v[92:95], v[128:131], v[220:223], v[92:95]
	v_mfma_f32_16x16x32_bf16 v[88:91], v[136:139], v[220:223], v[88:91]
	v_mfma_f32_16x16x32_bf16 v[84:87], v[128:131], v[228:231], v[84:87]
	v_mfma_f32_16x16x32_bf16 v[80:83], v[136:139], v[228:231], v[80:83]
	v_mfma_f32_16x16x32_bf16 v[76:79], v[128:131], v[236:239], v[76:79]
	v_mfma_f32_16x16x32_bf16 v[72:75], v[136:139], v[236:239], v[72:75]
	v_mfma_f32_16x16x32_bf16 v[68:71], v[128:131], v[244:247], v[68:71]
	v_mfma_f32_16x16x32_bf16 v[64:67], v[136:139], v[244:247], v[64:67]
	v_mfma_f32_16x16x32_bf16 v[92:95], v[132:135], v[224:227], v[92:95]
	v_mfma_f32_16x16x32_bf16 v[88:91], v[140:143], v[224:227], v[88:91]
	v_mfma_f32_16x16x32_bf16 v[84:87], v[132:135], v[232:235], v[84:87]
	v_mfma_f32_16x16x32_bf16 v[80:83], v[140:143], v[232:235], v[80:83]
	v_mfma_f32_16x16x32_bf16 v[76:79], v[132:135], v[240:243], v[76:79]
	v_mfma_f32_16x16x32_bf16 v[72:75], v[140:143], v[240:243], v[72:75]
	v_mfma_f32_16x16x32_bf16 v[68:71], v[132:135], v[248:251], v[68:71]
	v_mfma_f32_16x16x32_bf16 v[64:67], v[140:143], v[248:251], v[64:67]
	s_setprio 0
	s_setprio 1
	v_mfma_f32_16x16x32_bf16 v[28:31], v[144:147], v[220:223], v[28:31]
	v_mfma_f32_16x16x32_bf16 v[24:27], v[184:187], v[220:223], v[24:27]
	v_mfma_f32_16x16x32_bf16 v[20:23], v[144:147], v[228:231], v[20:23]
	v_mfma_f32_16x16x32_bf16 v[16:19], v[184:187], v[228:231], v[16:19]
	v_mfma_f32_16x16x32_bf16 v[12:15], v[144:147], v[236:239], v[12:15]
	v_mfma_f32_16x16x32_bf16 v[8:11], v[184:187], v[236:239], v[8:11]
	v_mfma_f32_16x16x32_bf16 v[4:7], v[144:147], v[244:247], v[4:7]
	v_mfma_f32_16x16x32_bf16 v[0:3], v[184:187], v[244:247], v[0:3]
	v_mfma_f32_16x16x32_bf16 v[28:31], v[148:151], v[224:227], v[28:31]
	v_mfma_f32_16x16x32_bf16 v[24:27], v[188:191], v[224:227], v[24:27]
	v_mfma_f32_16x16x32_bf16 v[20:23], v[148:151], v[232:235], v[20:23]
	v_mfma_f32_16x16x32_bf16 v[16:19], v[188:191], v[232:235], v[16:19]
	v_mfma_f32_16x16x32_bf16 v[12:15], v[148:151], v[240:243], v[12:15]
	v_mfma_f32_16x16x32_bf16 v[8:11], v[188:191], v[240:243], v[8:11]
	v_mfma_f32_16x16x32_bf16 v[4:7], v[148:151], v[248:251], v[4:7]
	v_mfma_f32_16x16x32_bf16 v[0:3], v[188:191], v[248:251], v[0:3]
	s_setprio 0
	s_barrier
	s_add_i32 s50, 0, 0x18000
	s_add_i32 s51, 0, 0x1c000
	v_add_u32_e32 v140, s50, v198
	v_add_u32_e32 v160, s51, v198
	ds_read_b128 v[128:131], v140
	ds_read_b128 v[132:135], v140 offset:1024
	ds_read_b128 v[136:139], v140 offset:2048
	ds_read_b128 v[140:143], v140 offset:3072
	ds_read_b128 v[144:147], v160
	ds_read_b128 v[148:151], v160 offset:1024
	ds_read_b128 v[184:187], v160 offset:2048
	ds_read_b128 v[188:191], v160 offset:3072
	s_add_u32 s46, s64, 0x40000
	s_addc_u32 s47, s65, 0
	s_mov_b32 m0, s71
	v_lshl_add_u64 v[212:213], s[46:47], 0, v[152:153]
	ds_read_b128 v[220:223], v209 offset:32768
	ds_read_b128 v[224:227], v209 offset:33792
	ds_read_b128 v[228:231], v209 offset:34816
	ds_read_b128 v[232:235], v209 offset:35840
	ds_read_b128 v[236:239], v209 offset:36864
	ds_read_b128 v[240:243], v209 offset:37888
	ds_read_b128 v[244:247], v209 offset:38912
	ds_read_b128 v[248:251], v209 offset:39936
	global_load_lds_dwordx4 v[212:213], off
	v_lshl_add_u64 v[212:213], s[46:47], 0, v[156:157]
	s_mov_b32 m0, s72
	s_nop 0
	global_load_lds_dwordx4 v[212:213], off
	s_nop 0
	s_waitcnt vmcnt(8)
	s_waitcnt lgkmcnt(0)
	s_barrier
	s_setprio 1
	s_waitcnt lgkmcnt(0)
	v_mfma_f32_16x16x32_bf16 v[124:127], v[128:131], v[220:223], v[124:127]
	v_mfma_f32_16x16x32_bf16 v[120:123], v[136:139], v[220:223], v[120:123]
	v_mfma_f32_16x16x32_bf16 v[116:119], v[128:131], v[228:231], v[116:119]
	v_mfma_f32_16x16x32_bf16 v[112:115], v[136:139], v[228:231], v[112:115]
	v_mfma_f32_16x16x32_bf16 v[108:111], v[128:131], v[236:239], v[108:111]
	v_mfma_f32_16x16x32_bf16 v[104:107], v[136:139], v[236:239], v[104:107]
	v_mfma_f32_16x16x32_bf16 v[100:103], v[128:131], v[244:247], v[100:103]
	v_mfma_f32_16x16x32_bf16 v[96:99], v[136:139], v[244:247], v[96:99]
	v_mfma_f32_16x16x32_bf16 v[124:127], v[132:135], v[224:227], v[124:127]
	v_mfma_f32_16x16x32_bf16 v[120:123], v[140:143], v[224:227], v[120:123]
	v_mfma_f32_16x16x32_bf16 v[116:119], v[132:135], v[232:235], v[116:119]
	v_mfma_f32_16x16x32_bf16 v[112:115], v[140:143], v[232:235], v[112:115]
	v_mfma_f32_16x16x32_bf16 v[108:111], v[132:135], v[240:243], v[108:111]
	v_mfma_f32_16x16x32_bf16 v[104:107], v[140:143], v[240:243], v[104:107]
	v_mfma_f32_16x16x32_bf16 v[100:103], v[132:135], v[248:251], v[100:103]
	v_mfma_f32_16x16x32_bf16 v[96:99], v[140:143], v[248:251], v[96:99]
	s_setprio 0
	s_setprio 1
	v_mfma_f32_16x16x32_bf16 v[60:63], v[144:147], v[220:223], v[60:63]
	v_mfma_f32_16x16x32_bf16 v[56:59], v[184:187], v[220:223], v[56:59]
	v_mfma_f32_16x16x32_bf16 v[52:55], v[144:147], v[228:231], v[52:55]
	v_mfma_f32_16x16x32_bf16 v[48:51], v[184:187], v[228:231], v[48:51]
	v_mfma_f32_16x16x32_bf16 v[44:47], v[144:147], v[236:239], v[44:47]
	v_mfma_f32_16x16x32_bf16 v[40:43], v[184:187], v[236:239], v[40:43]
	v_mfma_f32_16x16x32_bf16 v[36:39], v[144:147], v[244:247], v[36:39]
	v_mfma_f32_16x16x32_bf16 v[32:35], v[184:187], v[244:247], v[32:35]
	v_mfma_f32_16x16x32_bf16 v[60:63], v[148:151], v[224:227], v[60:63]
	v_mfma_f32_16x16x32_bf16 v[56:59], v[188:191], v[224:227], v[56:59]
	v_mfma_f32_16x16x32_bf16 v[52:55], v[148:151], v[232:235], v[52:55]
	v_mfma_f32_16x16x32_bf16 v[48:51], v[188:191], v[232:235], v[48:51]
	v_mfma_f32_16x16x32_bf16 v[44:47], v[148:151], v[240:243], v[44:47]
	v_mfma_f32_16x16x32_bf16 v[40:43], v[188:191], v[240:243], v[40:43]
	v_mfma_f32_16x16x32_bf16 v[36:39], v[148:151], v[248:251], v[36:39]
	v_mfma_f32_16x16x32_bf16 v[32:35], v[188:191], v[248:251], v[32:35]
	s_setprio 0
	s_barrier
	s_add_i32 s46, s50, s68
	v_lshl_add_u64 v[212:213], v[252:253], 0, s[16:17]
	s_mov_b32 m0, s46
	ds_read_b128 v[220:223], v209 offset:49152
	ds_read_b128 v[224:227], v209 offset:50176
	ds_read_b128 v[228:231], v209 offset:51200
	ds_read_b128 v[232:235], v209 offset:52224
	ds_read_b128 v[236:239], v209 offset:53248
	ds_read_b128 v[240:243], v209 offset:54272
	ds_read_b128 v[244:247], v209 offset:55296
	ds_read_b128 v[248:251], v209 offset:56320
	global_load_lds_dwordx4 v[212:213], off
	s_add_i32 m0, s46, 0x2000
	s_add_u32 s46, s62, 0x40080
	v_lshl_add_u64 v[202:203], v[202:203], 0, s[16:17]
	s_addc_u32 s47, s63, 0
	s_add_i32 s50, s51, s68
	global_load_lds_dwordx4 v[202:203], off
	v_lshl_add_u64 v[202:203], s[46:47], 0, v[154:155]
	s_mov_b32 m0, s50
	s_nop 0
	global_load_lds_dwordx4 v[202:203], off
	v_lshl_add_u64 v[202:203], s[46:47], 0, v[158:159]
	s_add_i32 m0, s50, 0x2000
	s_nop 0
	global_load_lds_dwordx4 v[202:203], off
	v_lshl_add_u64 v[202:203], v[204:205], 0, s[16:17]
	s_mov_b32 m0, s79
	s_nop 0
	global_load_lds_dwordx4 v[202:203], off
	v_lshl_add_u64 v[202:203], v[206:207], 0, s[16:17]
	s_mov_b32 m0, s80
	s_nop 0
	global_load_lds_dwordx4 v[202:203], off
	s_waitcnt vmcnt(8)
	s_waitcnt lgkmcnt(0)
	s_barrier
	s_setprio 1
	s_waitcnt lgkmcnt(0)
	v_mfma_f32_16x16x32_bf16 v[92:95], v[128:131], v[220:223], v[92:95]
	v_mfma_f32_16x16x32_bf16 v[88:91], v[136:139], v[220:223], v[88:91]
	v_mfma_f32_16x16x32_bf16 v[84:87], v[128:131], v[228:231], v[84:87]
	v_mfma_f32_16x16x32_bf16 v[80:83], v[136:139], v[228:231], v[80:83]
	v_mfma_f32_16x16x32_bf16 v[76:79], v[128:131], v[236:239], v[76:79]
	v_mfma_f32_16x16x32_bf16 v[72:75], v[136:139], v[236:239], v[72:75]
	v_mfma_f32_16x16x32_bf16 v[68:71], v[128:131], v[244:247], v[68:71]
	v_mfma_f32_16x16x32_bf16 v[64:67], v[136:139], v[244:247], v[64:67]
	v_mfma_f32_16x16x32_bf16 v[92:95], v[132:135], v[224:227], v[92:95]
	v_mfma_f32_16x16x32_bf16 v[88:91], v[140:143], v[224:227], v[88:91]
	v_mfma_f32_16x16x32_bf16 v[84:87], v[132:135], v[232:235], v[84:87]
	v_mfma_f32_16x16x32_bf16 v[80:83], v[140:143], v[232:235], v[80:83]
	v_mfma_f32_16x16x32_bf16 v[76:79], v[132:135], v[240:243], v[76:79]
	v_mfma_f32_16x16x32_bf16 v[72:75], v[140:143], v[240:243], v[72:75]
	v_mfma_f32_16x16x32_bf16 v[68:71], v[132:135], v[248:251], v[68:71]
	v_mfma_f32_16x16x32_bf16 v[64:67], v[140:143], v[248:251], v[64:67]
	s_setprio 0
	s_setprio 1
	v_mfma_f32_16x16x32_bf16 v[28:31], v[144:147], v[220:223], v[28:31]
	v_mfma_f32_16x16x32_bf16 v[24:27], v[184:187], v[220:223], v[24:27]
	v_mfma_f32_16x16x32_bf16 v[20:23], v[144:147], v[228:231], v[20:23]
	v_mfma_f32_16x16x32_bf16 v[16:19], v[184:187], v[228:231], v[16:19]
	v_mfma_f32_16x16x32_bf16 v[12:15], v[144:147], v[236:239], v[12:15]
	v_mfma_f32_16x16x32_bf16 v[8:11], v[184:187], v[236:239], v[8:11]
	v_mfma_f32_16x16x32_bf16 v[4:7], v[144:147], v[244:247], v[4:7]
	v_mfma_f32_16x16x32_bf16 v[0:3], v[184:187], v[244:247], v[0:3]
	v_mfma_f32_16x16x32_bf16 v[28:31], v[148:151], v[224:227], v[28:31]
	v_mfma_f32_16x16x32_bf16 v[24:27], v[188:191], v[224:227], v[24:27]
	v_mfma_f32_16x16x32_bf16 v[20:23], v[148:151], v[232:235], v[20:23]
	v_mfma_f32_16x16x32_bf16 v[16:19], v[188:191], v[232:235], v[16:19]
	v_mfma_f32_16x16x32_bf16 v[12:15], v[148:151], v[240:243], v[12:15]
	v_mfma_f32_16x16x32_bf16 v[8:11], v[188:191], v[240:243], v[8:11]
	v_mfma_f32_16x16x32_bf16 v[4:7], v[148:151], v[248:251], v[4:7]
	v_mfma_f32_16x16x32_bf16 v[0:3], v[188:191], v[248:251], v[0:3]
	s_setprio 0
	s_barrier
	s_add_i32 s49, s49, 2
	s_add_u32 s60, s60, 0x100
	s_addc_u32 s61, s61, 0
	s_add_u32 s43, s43, 0x100
	s_addc_u32 s48, s48, 0
	s_cmp_gt_u32 s49, 13
	s_cbranch_scc0 .LBB0_186
	s_and_b64 vcc, exec, s[18:19]
	s_cbranch_vccnz .LBB0_190
	s_lshl_b32 s4, s10, 8
	s_cmp_lt_i32 s58, 8
	s_mov_b64 s[10:11], -1
	s_cbranch_scc0 .LBB0_191

.LBB0_868:
	s_and_saveexec_b64 s[8:9], s[6:7]
	s_cbranch_execz .LBB0_872
	s_mov_b64 s[12:13], exec
	v_mbcnt_lo_u32_b32 v0, s12, 0
	v_mbcnt_hi_u32_b32 v0, s13, v0
	v_cmp_eq_u32_e32 vcc, 0, v0
	s_and_saveexec_b64 s[10:11], vcc
	s_cbranch_execz .LBB0_871
	s_bcnt1_i32_b64 s12, s[12:13]
	v_mov_b32_e32 v1, s12
	s_bitcmp1_b32 s98, 8
	s_cbranch_scc1 .Lmy_pf_have_p
	global_atomic_add v1, v177, v1, s[38:39] offset:512 sc0
	s_branch .LBB0_871
.Lmy_pf_have_p:
	s_waitcnt vmcnt(0)
	v_mov_b32_e32 v1, v250

.LBB0_878:
	s_and_saveexec_b64 s[46:47], s[6:7]
	s_cbranch_execz .Lmy_pf_skip_p
	v_mov_b32_e32 v250, 1
	global_atomic_add v250, v177, v250, s[38:39] offset:512 sc0
	s_bitset1_b32 s98, 8
.Lmy_pf_skip_p:
	s_or_b64 exec, exec, s[46:47]
	v_mov_b32_e32 v26, v186
	s_add_i32 s56, s8, s3
	v_and_b32_e32 v193, 31, v26
	v_or_b32_e32 v2, s56, v193
	v_mov_b64_e32 v[0:1], s[30:31]
	v_mad_i64_i32 v[0:1], s[8:9], v2, s48, v[0:1]
	s_max_i32 s8, s16, 0
	s_lshl_b32 s8, s8, 8
	v_bfe_u32 v192, v26, 5, 1
	s_mul_i32 s26, s15, 0x60
	s_add_i32 s8, s8, s3
	v_lshl_add_u64 v[0:1], s[26:27], 1, v[0:1]
	v_lshlrev_b32_e32 v176, 4, v192
	v_or_b32_e32 v195, s8, v193
	v_lshl_add_u64 v[4:5], v[0:1], 0, v[176:177]
	s_cmp_lt_i32 s16, 0
	v_lshlrev_b32_e32 v0, 5, v195
	v_add_u32_e32 v1, 0x200, v0
	s_cselect_b64 s[10:11], -1, 0
	global_load_dwordx4 v[16:19], v[4:5], off
	global_load_dwordx4 v[20:23], v[4:5], off offset:32
	global_load_dwordx4 v[28:31], v[4:5], off offset:64
	v_cndmask_b32_e64 v8, v1, v0, s[10:11]
	v_ashrrev_i32_e32 v9, 31, v8
	global_load_dwordx4 v[32:35], v[4:5], off offset:96
	v_lshlrev_b32_e32 v176, 5, v192
	v_lshl_add_u64 v[8:9], v[8:9], 2, s[52:53]
	v_lshl_add_u64 v[24:25], v[8:9], 0, v[176:177]
	global_load_dwordx4 v[0:3], v[4:5], off offset:128
	s_nop 0
	global_load_dwordx4 v[4:7], v[4:5], off offset:160
	s_nop 0
	global_load_dwordx4 v[8:11], v[24:25], off offset:16
	global_load_dwordx4 v[36:39], v[24:25], off
	global_load_dwordx4 v[12:15], v[24:25], off offset:80
	global_load_dwordx4 v[40:43], v[24:25], off offset:64
	v_ashrrev_i32_e32 v178, 3, v26
	v_ashrrev_i32_e32 v179, 31, v178
	s_cmp_gt_i32 s16, -1
	s_cselect_b64 s[62:63], -1, 0
	s_lshl_b32 s26, s15, 7
	v_ashrrev_i32_e32 v180, 2, v26
	v_cmp_gt_i32_e64 s[8:9], s49, v26
	v_mov_b32_e32 v136, v177
	v_mov_b32_e32 v137, v177
	v_mov_b32_e32 v138, v177
	v_mov_b32_e32 v139, v177
	v_ashrrev_i32_e32 v181, 31, v180
	s_waitcnt vmcnt(9)
	v_lshlrev_b32_e32 v24, 16, v16
	v_and_b32_e32 v16, 0xffff0000, v16
	v_lshlrev_b32_e32 v25, 16, v17
	v_and_b32_e32 v17, 0xffff0000, v17
	v_mul_f32_e32 v16, 0x3e16c740, v16
	v_mul_f32_e32 v17, 0x3e16c740, v17
	v_lshlrev_b32_e32 v27, 16, v18
	v_and_b32_e32 v18, 0xffff0000, v18
	v_lshlrev_b32_e32 v44, 16, v19
	v_and_b32_e32 v19, 0xffff0000, v19
	v_mul_f32_e32 v24, 0x3e16c740, v24
	v_mul_f32_e32 v25, 0x3e16c740, v25
	v_cvt_pk_bf16_f32 v112, v24, v16
	v_cvt_pk_bf16_f32 v113, v25, v17
	s_waitcnt vmcnt(7)
	v_lshlrev_b32_e32 v16, 16, v31
	v_and_b32_e32 v17, 0xffff0000, v31
	v_mul_f32_e32 v18, 0x3e16c740, v18
	v_mul_f32_e32 v19, 0x3e16c740, v19
	v_mul_f32_e32 v16, 0x3e16c740, v16
	v_mul_f32_e32 v17, 0x3e16c740, v17
	v_mul_f32_e32 v27, 0x3e16c740, v27
	v_mul_f32_e32 v44, 0x3e16c740, v44
	v_cvt_pk_bf16_f32 v114, v27, v18
	v_cvt_pk_bf16_f32 v115, v44, v19
	v_cvt_pk_bf16_f32 v123, v16, v17
	s_waitcnt vmcnt(6)
	v_lshlrev_b32_e32 v16, 16, v32
	v_and_b32_e32 v17, 0xffff0000, v32
	v_lshlrev_b32_e32 v18, 16, v33
	v_and_b32_e32 v19, 0xffff0000, v33
	v_mul_f32_e32 v16, 0x3e16c740, v16
	v_mul_f32_e32 v17, 0x3e16c740, v17
	v_mul_f32_e32 v18, 0x3e16c740, v18
	v_mul_f32_e32 v19, 0x3e16c740, v19
	v_cvt_pk_bf16_f32 v124, v16, v17
	v_cvt_pk_bf16_f32 v125, v18, v19
	s_waitcnt vmcnt(5)
	v_lshlrev_b32_e32 v17, 16, v0
	s_waitcnt vmcnt(4)
	v_lshlrev_b32_e32 v16, 16, v4
	s_waitcnt vmcnt(0)
	v_mov_b32_e32 v18, v40
	v_mov_b32_e32 v19, v36
	v_pk_mul_f32 v[18:19], v[18:19], v[16:17]
	v_lshlrev_b32_e32 v51, 16, v30
	v_sub_f32_e32 v18, v19, v18
	v_mul_f32_e32 v27, 0x3e16c740, v18
	v_mov_b32_e32 v18, v36
	v_mov_b32_e32 v19, v40
	v_and_b32_e32 v30, 0xffff0000, v30
	v_pk_mul_f32 v[16:17], v[18:19], v[16:17]
	v_mul_f32_e32 v30, 0x3e16c740, v30
	v_add_f32_e32 v16, v16, v17
	v_mul_f32_e32 v51, 0x3e16c740, v51
	v_cvt_pk_bf16_f32 v122, v51, v30
	v_mul_f32_e32 v30, 0x3e16c740, v16
	v_and_b32_e32 v17, 0xffff0000, v0
	v_and_b32_e32 v16, 0xffff0000, v4
	v_mov_b32_e32 v36, v41
	v_pk_mul_f32 v[18:19], v[36:37], v[16:17]
	v_mov_b32_e32 v40, v37
	v_sub_f32_e32 v0, v19, v18
	v_pk_mul_f32 v[16:17], v[40:41], v[16:17]
	v_lshlrev_b32_e32 v45, 16, v20
	v_and_b32_e32 v20, 0xffff0000, v20
	v_lshlrev_b32_e32 v46, 16, v21
	v_and_b32_e32 v21, 0xffff0000, v21
	v_lshlrev_b32_e32 v47, 16, v22
	v_and_b32_e32 v22, 0xffff0000, v22
	v_lshlrev_b32_e32 v48, 16, v23
	v_and_b32_e32 v23, 0xffff0000, v23
	v_mul_f32_e32 v31, 0x3e16c740, v0
	v_add_f32_e32 v0, v16, v17
	v_lshlrev_b64 v[16:17], 11, v[178:179]
	v_mul_f32_e32 v20, 0x3e16c740, v20
	v_mul_f32_e32 v21, 0x3e16c740, v21
	v_mul_f32_e32 v22, 0x3e16c740, v22
	v_mul_f32_e32 v23, 0x3e16c740, v23
	v_mul_f32_e32 v32, 0x3e16c740, v0
	v_and_b32_e32 v0, 7, v26
	v_lshl_add_u64 v[16:17], s[28:29], 0, v[16:17]
	v_mul_f32_e32 v45, 0x3e16c740, v45
	v_mul_f32_e32 v46, 0x3e16c740, v46
	v_mul_f32_e32 v47, 0x3e16c740, v47
	v_mul_f32_e32 v48, 0x3e16c740, v48
	v_cvt_pk_bf16_f32 v116, v45, v20
	v_cvt_pk_bf16_f32 v117, v46, v21
	v_cvt_pk_bf16_f32 v118, v47, v22
	v_cvt_pk_bf16_f32 v119, v48, v23
	v_lshlrev_b32_e32 v20, 16, v34
	v_and_b32_e32 v21, 0xffff0000, v34
	v_lshlrev_b32_e32 v22, 16, v35
	v_and_b32_e32 v23, 0xffff0000, v35
	v_lshl_add_u64 v[16:17], v[16:17], 0, s[26:27]
	v_lshlrev_b32_e32 v176, 4, v0
	v_mul_f32_e32 v20, 0x3e16c740, v20
	v_mul_f32_e32 v21, 0x3e16c740, v21
	v_mul_f32_e32 v22, 0x3e16c740, v22
	v_mul_f32_e32 v23, 0x3e16c740, v23
	v_lshl_add_u64 v[16:17], v[16:17], 0, v[176:177]
	v_cvt_pk_bf16_f32 v126, v20, v21
	v_cvt_pk_bf16_f32 v127, v22, v23
	global_load_dwordx4 v[20:23], v[16:17], off
	s_nop 0
	global_load_dwordx4 v[16:19], v[16:17], off offset:1024
	v_lshlrev_b32_e32 v49, 16, v28
	v_and_b32_e32 v28, 0xffff0000, v28
	v_lshlrev_b32_e32 v50, 16, v29
	v_and_b32_e32 v29, 0xffff0000, v29
	v_mul_f32_e32 v28, 0x3e16c740, v28
	v_mul_f32_e32 v29, 0x3e16c740, v29
	v_mul_f32_e32 v49, 0x3e16c740, v49
	v_mul_f32_e32 v50, 0x3e16c740, v50
	v_cvt_pk_bf16_f32 v120, v49, v28
	v_cvt_pk_bf16_f32 v121, v50, v29
	v_lshlrev_b32_e32 v25, 16, v1
	v_lshlrev_b32_e32 v24, 16, v5
	v_mov_b32_e32 v28, v42
	v_mov_b32_e32 v29, v38
	v_pk_mul_f32 v[28:29], v[28:29], v[24:25]
	v_cvt_pk_bf16_f32 v128, v27, v31
	v_cvt_pk_bf16_f32 v132, v30, v32
	s_nop 0
	v_sub_f32_e32 v4, v29, v28
	v_mov_b32_e32 v28, v38
	v_mov_b32_e32 v29, v42
	v_pk_mul_f32 v[24:25], v[28:29], v[24:25]
	v_mul_f32_e32 v33, 0x3e16c740, v4
	v_add_f32_e32 v4, v24, v25
	v_and_b32_e32 v25, 0xffff0000, v1
	v_and_b32_e32 v24, 0xffff0000, v5
	v_mov_b32_e32 v38, v43
	v_mul_f32_e32 v28, 0x3e16c740, v4
	v_pk_mul_f32 v[4:5], v[38:39], v[24:25]
	v_mov_b32_e32 v42, v39
	v_sub_f32_e32 v1, v5, v4
	v_pk_mul_f32 v[4:5], v[42:43], v[24:25]
	v_mov_b32_e32 v24, v12
	v_add_f32_e32 v4, v4, v5
	v_mul_f32_e32 v29, 0x3e16c740, v4
	v_lshlrev_b32_e32 v5, 16, v2
	v_lshlrev_b32_e32 v4, 16, v6
	v_mov_b32_e32 v25, v8
	v_pk_mul_f32 v[24:25], v[24:25], v[4:5]
	v_mul_f32_e32 v1, 0x3e16c740, v1
	v_sub_f32_e32 v24, v25, v24
	v_mul_f32_e32 v34, 0x3e16c740, v24
	v_mov_b32_e32 v24, v8
	v_mov_b32_e32 v25, v12
	v_pk_mul_f32 v[4:5], v[24:25], v[4:5]
	v_mov_b32_e32 v8, v13
	v_add_f32_e32 v4, v4, v5
	v_mul_f32_e32 v35, 0x3e16c740, v4
	v_and_b32_e32 v5, 0xffff0000, v2
	v_and_b32_e32 v4, 0xffff0000, v6
	v_pk_mul_f32 v[24:25], v[8:9], v[4:5]
	v_mov_b32_e32 v12, v9
	v_sub_f32_e32 v2, v25, v24
	v_pk_mul_f32 v[4:5], v[12:13], v[4:5]
	v_mul_f32_e32 v6, 0x3e16c740, v2
	v_add_f32_e32 v2, v4, v5
	v_lshlrev_b32_e32 v5, 16, v3
	v_lshlrev_b32_e32 v4, 16, v7
	v_mov_b32_e32 v8, v14
	v_mov_b32_e32 v9, v10
	v_pk_mul_f32 v[8:9], v[8:9], v[4:5]
	v_mul_f32_e32 v12, 0x3e16c740, v2
	v_sub_f32_e32 v2, v9, v8
	v_mov_b32_e32 v8, v10
	v_mov_b32_e32 v9, v14
	v_pk_mul_f32 v[4:5], v[8:9], v[4:5]
	v_mul_f32_e32 v13, 0x3e16c740, v2
	v_add_f32_e32 v2, v4, v5
	v_mul_f32_e32 v8, 0x3e16c740, v2
	v_and_b32_e32 v3, 0xffff0000, v3
	v_and_b32_e32 v2, 0xffff0000, v7
	v_mov_b32_e32 v10, v15
	v_mov_b32_e32 v14, v11
	v_pk_mul_f32 v[4:5], v[10:11], v[2:3]
	v_pk_mul_f32 v[2:3], v[14:15], v[2:3]
	v_cvt_pk_bf16_f32 v129, v33, v1
	v_and_b32_e32 v1, 3, v26
	v_sub_f32_e32 v4, v5, v4
	v_add_f32_e32 v2, v2, v3
	v_lshlrev_b32_e32 v24, 4, v1
	v_mul_f32_e32 v4, 0x3e16c740, v4
	v_mul_f32_e32 v2, 0x3e16c740, v2
	v_cvt_pk_bf16_f32 v130, v34, v6
	v_cvt_pk_bf16_f32 v131, v13, v4
	v_cvt_pk_bf16_f32 v133, v28, v29
	v_cvt_pk_bf16_f32 v134, v35, v12
	v_cvt_pk_bf16_f32 v135, v8, v2
	s_and_saveexec_b64 s[12:13], s[8:9]
	s_cbranch_execz .LBB0_880
	v_lshlrev_b64 v[2:3], 6, v[180:181]
	v_lshl_add_u64 v[2:3], s[54:55], 0, v[2:3]
	v_mov_b32_e32 v25, v177
	v_lshl_add_u64 v[2:3], v[2:3], 0, v[24:25]
	v_add_co_u32_e32 v2, vcc, 0x208000, v2
	s_nop 1
	v_addc_co_u32_e32 v3, vcc, 0, v3, vcc
	global_load_dwordx4 v[136:139], v[2:3], off

.LBB0_924:
	s_and_saveexec_b64 s[8:9], s[6:7]
	s_cbranch_execz .LBB0_928
	s_mov_b64 s[18:19], exec
	v_mbcnt_lo_u32_b32 v0, s18, 0
	v_mbcnt_hi_u32_b32 v0, s19, v0
	v_cmp_eq_u32_e32 vcc, 0, v0
	s_and_saveexec_b64 s[16:17], vcc
	s_cbranch_execz .LBB0_927
	s_bcnt1_i32_b64 s12, s[18:19]
	v_mov_b32_e32 v1, s12
	s_bitcmp1_b32 s98, 9
	s_cbranch_scc1 .Lmy_pf_have_g
	global_atomic_add v1, v16, v1, s[38:39] offset:768 sc0
	s_branch .LBB0_927
.Lmy_pf_have_g:
	s_waitcnt vmcnt(0)
	v_mov_b32_e32 v1, v160

.LBB0_928:
	s_or_b64 exec, exec, s[8:9]
	s_waitcnt lgkmcnt(0)
	s_barrier
	ds_read_b32 v0, v72
	s_mov_b64 s[8:9], -1
	s_waitcnt lgkmcnt(0)
	s_barrier
	v_cmp_lt_i32_e32 vcc, s28, v0
	v_readfirstlane_b32 s48, v0
	s_cbranch_vccnz .LBB0_923
	s_lshl_b32 s16, s48, 2
	s_cmp_eq_u32 s16, 0x7ffffffc
	s_cbranch_scc1 .LBB0_922
	s_and_saveexec_b64 s[52:53], s[6:7]
	s_cbranch_execz .Lmy_pf_skip_g
	v_mov_b32_e32 v160, 1
	global_atomic_add v160, v16, v160, s[38:39] offset:768 sc0
	s_bitset1_b32 s98, 9
.Lmy_pf_skip_g:
	s_or_b64 exec, exec, s[52:53]
	s_cmpk_gt_i32 s16, 0x7ff
	s_cselect_b64 s[18:19], -1, 0
	s_cmpk_lt_i32 s16, 0x800
	s_cselect_b64 s[20:21], -1, 0
	s_and_b64 s[8:9], s[20:21], exec
	s_cselect_b32 s12, 64, 16
	s_ashr_i32 s17, s16, 31
	s_lshl_b64 s[8:9], s[16:17], 14
	v_lshl_add_u64 v[0:1], v[60:61], 0, s[8:9]
	v_mov_b32_e32 v78, v186
	v_add_co_u32_e32 v2, vcc, 0x2000, v0
	v_mov_b32_e32 v18, v16
	s_nop 0
	v_addc_co_u32_e32 v3, vcc, 0, v1, vcc
	global_load_dwordx4 v[20:23], v[0:1], off
	global_load_dwordx4 v[24:27], v[2:3], off
	v_mov_b32_e32 v19, v16
	v_mov_b32_e32 v17, v16
	v_mov_b64_e32 v[50:51], v[18:19]
	v_mov_b64_e32 v[58:59], v[18:19]
	s_waitcnt vmcnt(5)
	v_mov_b64_e32 v[30:31], v[18:19]
	s_waitcnt vmcnt(4)
	v_mov_b64_e32 v[34:35], v[18:19]
	v_cmp_gt_i32_e32 vcc, s12, v63
	v_mov_b64_e32 v[48:49], v[16:17]
	v_mov_b64_e32 v[56:57], v[16:17]
	v_mov_b64_e32 v[28:29], v[16:17]
	v_mov_b64_e32 v[32:33], v[16:17]
	s_and_saveexec_b64 s[8:9], vcc
	s_cbranch_execz .LBB0_932
	s_lshl_b32 s12, s48, 4
	s_and_b32 s12, s12, 0x180
	s_and_b64 s[22:23], s[20:21], exec
	s_cselect_b32 s12, s12, 0
	s_lshl_b32 s22, s48, 6
	s_lshl_b32 s23, s48, 8
	s_and_b32 s22, s22, 0xfffff800
	s_and_b32 s23, s23, 0x700
	s_or_b32 s24, s22, s23
	s_and_b64 s[22:23], s[20:21], exec
	s_cselect_b32 s22, s24, 0x8200
	v_add_u32_e32 v2, s22, v63
	v_mov_b64_e32 v[0:1], s[10:11]
	v_mad_i64_i32 v[0:1], s[22:23], v2, s29, v[0:1]
	s_lshl_b32 s12, s12, 1
	v_lshl_add_u64 v[0:1], v[0:1], 0, s[12:13]
	v_mov_b32_e32 v67, v16
	v_lshl_add_u64 v[0:1], v[0:1], 0, v[66:67]
	global_load_dwordx4 v[28:31], v[0:1], off offset:1040
	global_load_dwordx4 v[32:35], v[0:1], off offset:1024
	global_load_dwordx4 v[48:51], v[0:1], off offset:2064
	global_load_dwordx4 v[56:59], v[0:1], off offset:2048

.LBB0_1076:
	s_ashr_i32 s29, s28, 31
	s_lshl_b64 s[30:31], s[28:29], 19
	s_add_u32 s30, s3, s30
	s_addc_u32 s31, s45, s31
	s_and_b64 s[40:41], s[6:7], exec
	s_cselect_b32 s29, s31, s53
	s_cselect_b32 s65, s30, s52
	s_ashr_i32 s27, s26, 31
	s_lshl_b64 s[40:41], s[26:27], 19
	s_add_u32 s40, s62, s40
	s_addc_u32 s41, s63, s41
	s_and_b64 s[46:47], s[6:7], exec
	s_cselect_b32 s27, s41, s55
	s_cselect_b32 s66, s40, s54
	s_add_u32 s52, s52, 0x40080
	s_addc_u32 s53, s53, 0
	s_add_u32 s67, s54, 0x100
	v_mov_b32_e32 v0, 0
	s_addc_u32 s68, s55, 0
	s_mov_b32 s69, -2
	v_mov_b32_e32 v1, v0
	v_mov_b32_e32 v2, v0
	v_mov_b32_e32 v3, v0
	v_mov_b32_e32 v4, v0
	v_mov_b32_e32 v5, v0
	v_mov_b32_e32 v6, v0
	v_mov_b32_e32 v7, v0
	v_mov_b32_e32 v16, v0
	v_mov_b32_e32 v17, v0
	v_mov_b32_e32 v18, v0
	v_mov_b32_e32 v19, v0
	v_mov_b32_e32 v20, v0
	v_mov_b32_e32 v21, v0
	v_mov_b32_e32 v22, v0
	v_mov_b32_e32 v23, v0
	v_mov_b32_e32 v32, v0
	v_mov_b32_e32 v33, v0
	v_mov_b32_e32 v34, v0
	v_mov_b32_e32 v35, v0
	v_mov_b32_e32 v36, v0
	v_mov_b32_e32 v37, v0
	v_mov_b32_e32 v38, v0
	v_mov_b32_e32 v39, v0
	v_mov_b32_e32 v48, v0
	v_mov_b32_e32 v49, v0
	v_mov_b32_e32 v50, v0
	v_mov_b32_e32 v51, v0
	v_mov_b32_e32 v52, v0
	v_mov_b32_e32 v53, v0
	v_mov_b32_e32 v54, v0
	v_mov_b32_e32 v55, v0
	v_mov_b32_e32 v8, v0
	v_mov_b32_e32 v9, v0
	v_mov_b32_e32 v10, v0
	v_mov_b32_e32 v11, v0
	v_mov_b32_e32 v12, v0
	v_mov_b32_e32 v13, v0
	v_mov_b32_e32 v14, v0
	v_mov_b32_e32 v15, v0
	v_mov_b32_e32 v24, v0
	v_mov_b32_e32 v25, v0
	v_mov_b32_e32 v26, v0
	v_mov_b32_e32 v27, v0
	v_mov_b32_e32 v28, v0
	v_mov_b32_e32 v29, v0
	v_mov_b32_e32 v30, v0
	v_mov_b32_e32 v31, v0
	v_mov_b32_e32 v40, v0
	v_mov_b32_e32 v41, v0
	v_mov_b32_e32 v42, v0
	v_mov_b32_e32 v43, v0
	v_mov_b32_e32 v44, v0
	v_mov_b32_e32 v45, v0
	v_mov_b32_e32 v46, v0
	v_mov_b32_e32 v47, v0
	v_mov_b32_e32 v56, v0
	v_mov_b32_e32 v57, v0
	v_mov_b32_e32 v58, v0
	v_mov_b32_e32 v59, v0
	v_mov_b32_e32 v60, v0
	v_mov_b32_e32 v61, v0
	v_mov_b32_e32 v62, v0
	v_mov_b32_e32 v63, v0
	v_mov_b32_e32 v64, v0
	v_mov_b32_e32 v65, v0
	v_mov_b32_e32 v66, v0
	v_mov_b32_e32 v67, v0
	v_mov_b32_e32 v68, v0
	v_mov_b32_e32 v69, v0
	v_mov_b32_e32 v70, v0
	v_mov_b32_e32 v71, v0
	v_mov_b32_e32 v80, v0
	v_mov_b32_e32 v81, v0
	v_mov_b32_e32 v82, v0
	v_mov_b32_e32 v83, v0
	v_mov_b32_e32 v84, v0
	v_mov_b32_e32 v85, v0
	v_mov_b32_e32 v86, v0
	v_mov_b32_e32 v87, v0
	v_mov_b32_e32 v96, v0
	v_mov_b32_e32 v97, v0
	v_mov_b32_e32 v98, v0
	v_mov_b32_e32 v99, v0
	v_mov_b32_e32 v100, v0
	v_mov_b32_e32 v101, v0
	v_mov_b32_e32 v102, v0
	v_mov_b32_e32 v103, v0
	v_mov_b32_e32 v112, v0
	v_mov_b32_e32 v113, v0
	v_mov_b32_e32 v114, v0
	v_mov_b32_e32 v115, v0
	v_mov_b32_e32 v116, v0
	v_mov_b32_e32 v117, v0
	v_mov_b32_e32 v118, v0
	v_mov_b32_e32 v119, v0
	v_mov_b32_e32 v72, v0
	v_mov_b32_e32 v73, v0
	v_mov_b32_e32 v74, v0
	v_mov_b32_e32 v75, v0
	v_mov_b32_e32 v76, v0
	v_mov_b32_e32 v77, v0
	v_mov_b32_e32 v78, v0
	v_mov_b32_e32 v79, v0
	v_mov_b32_e32 v88, v0
	v_mov_b32_e32 v89, v0
	v_mov_b32_e32 v90, v0
	v_mov_b32_e32 v91, v0
	v_mov_b32_e32 v92, v0
	v_mov_b32_e32 v93, v0
	v_mov_b32_e32 v94, v0
	v_mov_b32_e32 v95, v0
	v_mov_b32_e32 v104, v0
	v_mov_b32_e32 v105, v0
	v_mov_b32_e32 v106, v0
	v_mov_b32_e32 v107, v0
	v_mov_b32_e32 v108, v0
	v_mov_b32_e32 v109, v0
	v_mov_b32_e32 v110, v0
	v_mov_b32_e32 v111, v0
	v_mov_b32_e32 v120, v0
	v_mov_b32_e32 v121, v0
	v_mov_b32_e32 v122, v0
	v_mov_b32_e32 v123, v0
	v_mov_b32_e32 v124, v0
	v_mov_b32_e32 v125, v0
	v_mov_b32_e32 v126, v0
	v_mov_b32_e32 v127, v0
	s_nop 0
	s_nop 0
	s_nop 0
	s_nop 0
	s_nop 0
	s_nop 0
.LBB0_1077:
	ds_read_b128 v[144:147], v154
	ds_read_b128 v[158:161], v154 offset:1024
	ds_read_b128 v[162:165], v154 offset:2048
	ds_read_b128 v[166:169], v154 offset:3072
	ds_read_b128 v[170:173], v155
	ds_read_b128 v[174:177], v155 offset:1024
	ds_read_b128 v[178:181], v155 offset:2048
	ds_read_b128 v[182:185], v155 offset:3072
	s_add_u32 s46, s52, 0xfffc0080
	s_addc_u32 s47, s53, -1
	s_cmp_eq_u32 s69, 12
	s_cselect_b32 s57, s29, s47
	s_cselect_b32 s56, s65, s46
	s_cselect_b32 s55, s27, s68
	s_cselect_b32 s54, s66, s67
	v_lshl_add_u64 v[148:149], s[52:53], 0, v[136:137]
	s_add_i32 m0, s43, 0xc000
	ds_read_b128 v[186:189], v156
	ds_read_b128 v[190:193], v156 offset:1024
	ds_read_b128 v[198:201], v156 offset:2048
	ds_read_b128 v[202:205], v156 offset:3072
	ds_read_b128 v[206:209], v156 offset:4096
	ds_read_b128 v[210:213], v156 offset:5120
	ds_read_b128 v[214:217], v156 offset:6144
	ds_read_b128 v[218:221], v156 offset:7168
	global_load_lds_dwordx4 v[148:149], off
	v_lshl_add_u64 v[148:149], s[52:53], 0, v[138:139]
	s_add_i32 m0, s43, 0xe000
	s_nop 0
	global_load_lds_dwordx4 v[148:149], off
	s_waitcnt vmcnt(8)
	s_waitcnt lgkmcnt(0)
	s_barrier
	s_setprio 1
	s_waitcnt lgkmcnt(0)
	v_mfma_f32_16x16x32_bf16 v[124:127], v[144:147], v[186:189], v[124:127]
	v_mfma_f32_16x16x32_bf16 v[120:123], v[162:165], v[186:189], v[120:123]
	v_mfma_f32_16x16x32_bf16 v[108:111], v[144:147], v[198:201], v[108:111]
	v_mfma_f32_16x16x32_bf16 v[104:107], v[162:165], v[198:201], v[104:107]
	v_mfma_f32_16x16x32_bf16 v[92:95], v[144:147], v[206:209], v[92:95]
	v_mfma_f32_16x16x32_bf16 v[88:91], v[162:165], v[206:209], v[88:91]
	v_mfma_f32_16x16x32_bf16 v[76:79], v[144:147], v[214:217], v[76:79]
	v_mfma_f32_16x16x32_bf16 v[72:75], v[162:165], v[214:217], v[72:75]
	v_mfma_f32_16x16x32_bf16 v[124:127], v[158:161], v[190:193], v[124:127]
	v_mfma_f32_16x16x32_bf16 v[120:123], v[166:169], v[190:193], v[120:123]
	v_mfma_f32_16x16x32_bf16 v[108:111], v[158:161], v[202:205], v[108:111]
	v_mfma_f32_16x16x32_bf16 v[104:107], v[166:169], v[202:205], v[104:107]
	v_mfma_f32_16x16x32_bf16 v[92:95], v[158:161], v[210:213], v[92:95]
	v_mfma_f32_16x16x32_bf16 v[88:91], v[166:169], v[210:213], v[88:91]
	v_mfma_f32_16x16x32_bf16 v[76:79], v[158:161], v[218:221], v[76:79]
	v_mfma_f32_16x16x32_bf16 v[72:75], v[166:169], v[218:221], v[72:75]
	s_setprio 0
	s_setprio 1
	v_mfma_f32_16x16x32_bf16 v[116:119], v[170:173], v[186:189], v[116:119]
	v_mfma_f32_16x16x32_bf16 v[112:115], v[178:181], v[186:189], v[112:115]
	v_mfma_f32_16x16x32_bf16 v[100:103], v[170:173], v[198:201], v[100:103]
	v_mfma_f32_16x16x32_bf16 v[96:99], v[178:181], v[198:201], v[96:99]
	v_mfma_f32_16x16x32_bf16 v[84:87], v[170:173], v[206:209], v[84:87]
	v_mfma_f32_16x16x32_bf16 v[80:83], v[178:181], v[206:209], v[80:83]
	v_mfma_f32_16x16x32_bf16 v[68:71], v[170:173], v[214:217], v[68:71]
	v_mfma_f32_16x16x32_bf16 v[64:67], v[178:181], v[214:217], v[64:67]
	v_mfma_f32_16x16x32_bf16 v[116:119], v[174:177], v[190:193], v[116:119]
	v_mfma_f32_16x16x32_bf16 v[112:115], v[182:185], v[190:193], v[112:115]
	v_mfma_f32_16x16x32_bf16 v[100:103], v[174:177], v[202:205], v[100:103]
	v_mfma_f32_16x16x32_bf16 v[96:99], v[182:185], v[202:205], v[96:99]
	v_mfma_f32_16x16x32_bf16 v[84:87], v[174:177], v[210:213], v[84:87]
	v_mfma_f32_16x16x32_bf16 v[80:83], v[182:185], v[210:213], v[80:83]
	v_mfma_f32_16x16x32_bf16 v[68:71], v[174:177], v[218:221], v[68:71]
	v_mfma_f32_16x16x32_bf16 v[64:67], v[182:185], v[218:221], v[64:67]
	s_setprio 0
	s_barrier
	s_add_i32 s46, s61, s4
	v_lshl_add_u64 v[148:149], s[54:55], 0, v[132:133]
	s_mov_b32 m0, s46
	ds_read_b128 v[186:189], v156 offset:16384
	ds_read_b128 v[190:193], v156 offset:17408
	ds_read_b128 v[198:201], v156 offset:18432
	ds_read_b128 v[202:205], v156 offset:19456
	ds_read_b128 v[206:209], v156 offset:20480
	ds_read_b128 v[210:213], v156 offset:21504
	ds_read_b128 v[214:217], v156 offset:22528
	ds_read_b128 v[218:221], v156 offset:23552
	global_load_lds_dwordx4 v[148:149], off
	s_add_i32 m0, s46, 0x2000
	s_add_u32 s46, s54, 0x40000
	v_lshl_add_u64 v[194:195], s[54:55], 0, v[128:129]
	s_addc_u32 s47, s55, 0
	s_add_i32 s70, s64, s4
	global_load_lds_dwordx4 v[194:195], off
	v_lshl_add_u64 v[196:197], s[46:47], 0, v[132:133]
	s_mov_b32 m0, s70
	v_lshl_add_u64 v[222:223], s[56:57], 0, v[130:131]
	global_load_lds_dwordx4 v[196:197], off
	v_lshl_add_u64 v[196:197], s[46:47], 0, v[128:129]
	s_add_i32 m0, s70, 0x2000
	s_nop 0
	global_load_lds_dwordx4 v[196:197], off
	v_lshl_add_u64 v[196:197], s[56:57], 0, v[134:135]
	s_mov_b32 m0, s43
	s_nop 0
	global_load_lds_dwordx4 v[196:197], off
	s_mov_b32 m0, s48
	s_nop 0
	global_load_lds_dwordx4 v[222:223], off
	s_nop 0
	s_waitcnt vmcnt(8)
	s_waitcnt lgkmcnt(0)
	s_barrier
	s_setprio 1
	s_waitcnt lgkmcnt(0)
	v_mfma_f32_16x16x32_bf16 v[60:63], v[144:147], v[186:189], v[60:63]
	v_mfma_f32_16x16x32_bf16 v[56:59], v[162:165], v[186:189], v[56:59]
	v_mfma_f32_16x16x32_bf16 v[44:47], v[144:147], v[198:201], v[44:47]
	v_mfma_f32_16x16x32_bf16 v[40:43], v[162:165], v[198:201], v[40:43]
	v_mfma_f32_16x16x32_bf16 v[28:31], v[144:147], v[206:209], v[28:31]
	v_mfma_f32_16x16x32_bf16 v[24:27], v[162:165], v[206:209], v[24:27]
	v_mfma_f32_16x16x32_bf16 v[12:15], v[144:147], v[214:217], v[12:15]
	v_mfma_f32_16x16x32_bf16 v[8:11], v[162:165], v[214:217], v[8:11]
	v_mfma_f32_16x16x32_bf16 v[60:63], v[158:161], v[190:193], v[60:63]
	v_mfma_f32_16x16x32_bf16 v[56:59], v[166:169], v[190:193], v[56:59]
	v_mfma_f32_16x16x32_bf16 v[44:47], v[158:161], v[202:205], v[44:47]
	v_mfma_f32_16x16x32_bf16 v[40:43], v[166:169], v[202:205], v[40:43]
	v_mfma_f32_16x16x32_bf16 v[28:31], v[158:161], v[210:213], v[28:31]
	v_mfma_f32_16x16x32_bf16 v[24:27], v[166:169], v[210:213], v[24:27]
	v_mfma_f32_16x16x32_bf16 v[12:15], v[158:161], v[218:221], v[12:15]
	v_mfma_f32_16x16x32_bf16 v[8:11], v[166:169], v[218:221], v[8:11]
	s_setprio 0
	s_setprio 1
	v_mfma_f32_16x16x32_bf16 v[52:55], v[170:173], v[186:189], v[52:55]
	v_mfma_f32_16x16x32_bf16 v[48:51], v[178:181], v[186:189], v[48:51]
	v_mfma_f32_16x16x32_bf16 v[36:39], v[170:173], v[198:201], v[36:39]
	v_mfma_f32_16x16x32_bf16 v[32:35], v[178:181], v[198:201], v[32:35]
	v_mfma_f32_16x16x32_bf16 v[20:23], v[170:173], v[206:209], v[20:23]
	v_mfma_f32_16x16x32_bf16 v[16:19], v[178:181], v[206:209], v[16:19]
	v_mfma_f32_16x16x32_bf16 v[4:7], v[170:173], v[214:217], v[4:7]
	v_mfma_f32_16x16x32_bf16 v[0:3], v[178:181], v[214:217], v[0:3]
	v_mfma_f32_16x16x32_bf16 v[52:55], v[174:177], v[190:193], v[52:55]
	v_mfma_f32_16x16x32_bf16 v[48:51], v[182:185], v[190:193], v[48:51]
	v_mfma_f32_16x16x32_bf16 v[36:39], v[174:177], v[202:205], v[36:39]
	v_mfma_f32_16x16x32_bf16 v[32:35], v[182:185], v[202:205], v[32:35]
	v_mfma_f32_16x16x32_bf16 v[20:23], v[174:177], v[210:213], v[20:23]
	v_mfma_f32_16x16x32_bf16 v[16:19], v[182:185], v[210:213], v[16:19]
	v_mfma_f32_16x16x32_bf16 v[4:7], v[174:177], v[218:221], v[4:7]
	v_mfma_f32_16x16x32_bf16 v[0:3], v[182:185], v[218:221], v[0:3]
	s_setprio 0
	s_barrier
	s_add_i32 s70, 0, 0x18000
	v_add_u32_e32 v157, s70, v152
	s_add_i32 s71, 0, 0x1c000
	ds_read_b128 v[144:147], v157
	ds_read_b128 v[158:161], v157 offset:1024
	ds_read_b128 v[162:165], v157 offset:2048
	ds_read_b128 v[166:169], v157 offset:3072
	v_add_u32_e32 v157, s71, v152
	ds_read_b128 v[170:173], v157
	ds_read_b128 v[174:177], v157 offset:1024
	ds_read_b128 v[178:181], v157 offset:2048
	ds_read_b128 v[182:185], v157 offset:3072
	s_add_u32 s46, s56, 0x40000
	s_addc_u32 s47, s57, 0
	s_mov_b32 m0, s49
	v_lshl_add_u64 v[224:225], s[46:47], 0, v[134:135]
	ds_read_b128 v[186:189], v156 offset:32768
	ds_read_b128 v[190:193], v156 offset:33792
	ds_read_b128 v[198:201], v156 offset:34816
	ds_read_b128 v[202:205], v156 offset:35840
	ds_read_b128 v[206:209], v156 offset:36864
	ds_read_b128 v[210:213], v156 offset:37888
	ds_read_b128 v[214:217], v156 offset:38912
	ds_read_b128 v[218:221], v156 offset:39936
	global_load_lds_dwordx4 v[224:225], off
	v_lshl_add_u64 v[224:225], s[46:47], 0, v[130:131]
	s_mov_b32 m0, s50
	s_nop 0
	global_load_lds_dwordx4 v[224:225], off
	s_nop 0
	s_waitcnt vmcnt(8)
	s_waitcnt lgkmcnt(0)
	s_barrier
	s_setprio 1
	s_waitcnt lgkmcnt(0)
	v_mfma_f32_16x16x32_bf16 v[124:127], v[144:147], v[186:189], v[124:127]
	v_mfma_f32_16x16x32_bf16 v[120:123], v[162:165], v[186:189], v[120:123]
	v_mfma_f32_16x16x32_bf16 v[108:111], v[144:147], v[198:201], v[108:111]
	v_mfma_f32_16x16x32_bf16 v[104:107], v[162:165], v[198:201], v[104:107]
	v_mfma_f32_16x16x32_bf16 v[92:95], v[144:147], v[206:209], v[92:95]
	v_mfma_f32_16x16x32_bf16 v[88:91], v[162:165], v[206:209], v[88:91]
	v_mfma_f32_16x16x32_bf16 v[76:79], v[144:147], v[214:217], v[76:79]
	v_mfma_f32_16x16x32_bf16 v[72:75], v[162:165], v[214:217], v[72:75]
	v_mfma_f32_16x16x32_bf16 v[124:127], v[158:161], v[190:193], v[124:127]
	v_mfma_f32_16x16x32_bf16 v[120:123], v[166:169], v[190:193], v[120:123]
	v_mfma_f32_16x16x32_bf16 v[108:111], v[158:161], v[202:205], v[108:111]
	v_mfma_f32_16x16x32_bf16 v[104:107], v[166:169], v[202:205], v[104:107]
	v_mfma_f32_16x16x32_bf16 v[92:95], v[158:161], v[210:213], v[92:95]
	v_mfma_f32_16x16x32_bf16 v[88:91], v[166:169], v[210:213], v[88:91]
	v_mfma_f32_16x16x32_bf16 v[76:79], v[158:161], v[218:221], v[76:79]
	v_mfma_f32_16x16x32_bf16 v[72:75], v[166:169], v[218:221], v[72:75]
	s_setprio 0
	s_setprio 1
	v_mfma_f32_16x16x32_bf16 v[116:119], v[170:173], v[186:189], v[116:119]
	v_mfma_f32_16x16x32_bf16 v[112:115], v[178:181], v[186:189], v[112:115]
	v_mfma_f32_16x16x32_bf16 v[100:103], v[170:173], v[198:201], v[100:103]
	v_mfma_f32_16x16x32_bf16 v[96:99], v[178:181], v[198:201], v[96:99]
	v_mfma_f32_16x16x32_bf16 v[84:87], v[170:173], v[206:209], v[84:87]
	v_mfma_f32_16x16x32_bf16 v[80:83], v[178:181], v[206:209], v[80:83]
	v_mfma_f32_16x16x32_bf16 v[68:71], v[170:173], v[214:217], v[68:71]
	v_mfma_f32_16x16x32_bf16 v[64:67], v[178:181], v[214:217], v[64:67]
	v_mfma_f32_16x16x32_bf16 v[116:119], v[174:177], v[190:193], v[116:119]
	v_mfma_f32_16x16x32_bf16 v[112:115], v[182:185], v[190:193], v[112:115]
	v_mfma_f32_16x16x32_bf16 v[100:103], v[174:177], v[202:205], v[100:103]
	v_mfma_f32_16x16x32_bf16 v[96:99], v[182:185], v[202:205], v[96:99]
	v_mfma_f32_16x16x32_bf16 v[84:87], v[174:177], v[210:213], v[84:87]
	v_mfma_f32_16x16x32_bf16 v[80:83], v[182:185], v[210:213], v[80:83]
	v_mfma_f32_16x16x32_bf16 v[68:71], v[174:177], v[218:221], v[68:71]
	v_mfma_f32_16x16x32_bf16 v[64:67], v[182:185], v[218:221], v[64:67]
	s_setprio 0
	s_barrier
	s_add_i32 s46, s70, s4
	v_lshl_add_u64 v[148:149], v[148:149], 0, s[16:17]
	s_mov_b32 m0, s46
	ds_read_b128 v[186:189], v156 offset:49152
	ds_read_b128 v[190:193], v156 offset:50176
	ds_read_b128 v[198:201], v156 offset:51200
	ds_read_b128 v[202:205], v156 offset:52224
	ds_read_b128 v[206:209], v156 offset:53248
	ds_read_b128 v[210:213], v156 offset:54272
	ds_read_b128 v[214:217], v156 offset:55296
	ds_read_b128 v[218:221], v156 offset:56320
	global_load_lds_dwordx4 v[148:149], off
	s_add_i32 m0, s46, 0x2000
	s_add_u32 s46, s54, 0x40080
	v_lshl_add_u64 v[148:149], v[194:195], 0, s[16:17]
	s_addc_u32 s47, s55, 0
	s_add_i32 s54, s71, s4
	global_load_lds_dwordx4 v[148:149], off
	v_lshl_add_u64 v[148:149], s[46:47], 0, v[132:133]
	s_mov_b32 m0, s54
	s_nop 0
	global_load_lds_dwordx4 v[148:149], off
	v_lshl_add_u64 v[148:149], s[46:47], 0, v[128:129]
	s_add_i32 m0, s54, 0x2000
	s_nop 0
	global_load_lds_dwordx4 v[148:149], off
	v_lshl_add_u64 v[148:149], v[196:197], 0, s[16:17]
	s_mov_b32 m0, s58
	s_nop 0
	global_load_lds_dwordx4 v[148:149], off
	v_lshl_add_u64 v[148:149], v[222:223], 0, s[16:17]
	s_mov_b32 m0, s59
	s_nop 0
	global_load_lds_dwordx4 v[148:149], off
	s_waitcnt vmcnt(8)
	s_waitcnt lgkmcnt(0)
	s_barrier
	s_setprio 1
	s_waitcnt lgkmcnt(0)
	v_mfma_f32_16x16x32_bf16 v[60:63], v[144:147], v[186:189], v[60:63]
	v_mfma_f32_16x16x32_bf16 v[56:59], v[162:165], v[186:189], v[56:59]
	v_mfma_f32_16x16x32_bf16 v[44:47], v[144:147], v[198:201], v[44:47]
	v_mfma_f32_16x16x32_bf16 v[40:43], v[162:165], v[198:201], v[40:43]
	v_mfma_f32_16x16x32_bf16 v[28:31], v[144:147], v[206:209], v[28:31]
	v_mfma_f32_16x16x32_bf16 v[24:27], v[162:165], v[206:209], v[24:27]
	v_mfma_f32_16x16x32_bf16 v[12:15], v[144:147], v[214:217], v[12:15]
	v_mfma_f32_16x16x32_bf16 v[8:11], v[162:165], v[214:217], v[8:11]
	v_mfma_f32_16x16x32_bf16 v[60:63], v[158:161], v[190:193], v[60:63]
	v_mfma_f32_16x16x32_bf16 v[56:59], v[166:169], v[190:193], v[56:59]
	v_mfma_f32_16x16x32_bf16 v[44:47], v[158:161], v[202:205], v[44:47]
	v_mfma_f32_16x16x32_bf16 v[40:43], v[166:169], v[202:205], v[40:43]
	v_mfma_f32_16x16x32_bf16 v[28:31], v[158:161], v[210:213], v[28:31]
	v_mfma_f32_16x16x32_bf16 v[24:27], v[166:169], v[210:213], v[24:27]
	v_mfma_f32_16x16x32_bf16 v[12:15], v[158:161], v[218:221], v[12:15]
	v_mfma_f32_16x16x32_bf16 v[8:11], v[166:169], v[218:221], v[8:11]
	s_setprio 0
	s_setprio 1
	v_mfma_f32_16x16x32_bf16 v[52:55], v[170:173], v[186:189], v[52:55]
	v_mfma_f32_16x16x32_bf16 v[48:51], v[178:181], v[186:189], v[48:51]
	v_mfma_f32_16x16x32_bf16 v[36:39], v[170:173], v[198:201], v[36:39]
	v_mfma_f32_16x16x32_bf16 v[32:35], v[178:181], v[198:201], v[32:35]
	v_mfma_f32_16x16x32_bf16 v[20:23], v[170:173], v[206:209], v[20:23]
	v_mfma_f32_16x16x32_bf16 v[16:19], v[178:181], v[206:209], v[16:19]
	v_mfma_f32_16x16x32_bf16 v[4:7], v[170:173], v[214:217], v[4:7]
	v_mfma_f32_16x16x32_bf16 v[0:3], v[178:181], v[214:217], v[0:3]
	v_mfma_f32_16x16x32_bf16 v[52:55], v[174:177], v[190:193], v[52:55]
	v_mfma_f32_16x16x32_bf16 v[48:51], v[182:185], v[190:193], v[48:51]
	v_mfma_f32_16x16x32_bf16 v[36:39], v[174:177], v[202:205], v[36:39]
	v_mfma_f32_16x16x32_bf16 v[32:35], v[182:185], v[202:205], v[32:35]
	v_mfma_f32_16x16x32_bf16 v[20:23], v[174:177], v[210:213], v[20:23]
	v_mfma_f32_16x16x32_bf16 v[16:19], v[182:185], v[210:213], v[16:19]
	v_mfma_f32_16x16x32_bf16 v[4:7], v[174:177], v[218:221], v[4:7]
	v_mfma_f32_16x16x32_bf16 v[0:3], v[182:185], v[218:221], v[0:3]
	s_setprio 0
	s_barrier
	s_add_i32 s69, s69, 2
	s_add_u32 s52, s52, 0x100
	s_addc_u32 s53, s53, 0
	s_add_u32 s67, s67, 0x100
	s_addc_u32 s68, s68, 0
	s_cmp_gt_u32 s69, 13
	s_cbranch_scc0 .LBB0_1077
	s_and_b64 vcc, exec, s[18:19]
	s_cbranch_vccz .LBB0_1080
	s_barrier
